# RG-LRU scan block-parallel: 4 waves per direction scan 16-token blocks in registers (h_local, decay product), exchange aggregates via LDS, fix-up; replaces single-wave 64-step scan
# speedup vs baseline: 1.0172x; 1.0172x over previous
.LBB0_270:
	s_waitcnt lgkmcnt(0)
	s_barrier
	ds_read_b128 v[40:43], v117
	ds_read_b128 v[36:39], v117 offset:64
	ds_read_b128 v[44:47], v118 offset:9216
	ds_read_b128 v[48:51], v118 offset:18432
	ds_read_b128 v[52:55], v118 offset:9280
	s_waitcnt lgkmcnt(2)
	v_mfma_f32_16x16x32_bf16 v[44:47], v[40:43], v[44:47], 0
	ds_read_u16 v3, v119
	s_waitcnt lgkmcnt(0)
	v_lshlrev_b32_e32 v3, 16, v3
	v_mfma_f32_16x16x32_bf16 v[44:47], v[36:39], v[52:55], v[44:47]
	ds_read_b128 v[52:55], v118 offset:18496
	v_mfma_f32_16x16x32_bf16 v[48:51], v[40:43], v[48:51], 0
	s_waitcnt lgkmcnt(0)
	v_mfma_f32_16x16x32_bf16 v[48:51], v[36:39], v[52:55], v[48:51]
	s_nop 3
	v_add_f32_e32 v1, v97, v44
	v_mul_f32_e32 v1, 0xbfb8aa3b, v1
	v_exp_f32_e32 v1, v1
	s_nop 0
	v_add_f32_e32 v1, 1.0, v1
	v_rcp_f32_e32 v1, v1
	v_add_f32_e32 v2, v98, v48
	v_mul_f32_e32 v2, 0xbfb8aa3b, v2
	v_exp_f32_e32 v2, v2
	v_mul_f32_e32 v1, v105, v1
	v_mul_f32_e32 v1, 0x3fb8aa3b, v1
	v_exp_f32_e32 v1, v1
	v_add_f32_e32 v2, 1.0, v2
	v_rcp_f32_e32 v2, v2
	v_fma_f32 v44, -v1, v1, 1.0
	v_max_f32_e32 v44, 0, v44
	v_sqrt_f32_e32 v44, v44
	v_mul_f32_e32 v2, v2, v3
	v_mul_f32_e32 v2, v2, v44
	ds_write_b32 v109, v1 offset:27648
	ds_write_b32 v109, v2 offset:44288
	v_add_f32_e32 v1, v97, v45
	v_mul_f32_e32 v1, 0xbfb8aa3b, v1
	v_exp_f32_e32 v1, v1
	v_add_f32_e32 v2, v98, v49
	v_mul_f32_e32 v2, 0xbfb8aa3b, v2
	v_exp_f32_e32 v2, v2
	v_add_f32_e32 v1, 1.0, v1
	v_rcp_f32_e32 v1, v1
	ds_read_u16 v3, v120
	v_add_f32_e32 v2, 1.0, v2
	v_rcp_f32_e32 v2, v2
	v_mul_f32_e32 v1, v105, v1
	v_mul_f32_e32 v1, 0x3fb8aa3b, v1
	v_exp_f32_e32 v1, v1
	s_waitcnt lgkmcnt(0)
	v_lshlrev_b32_e32 v3, 16, v3
	v_mul_f32_e32 v2, v2, v3
	ds_read_u16 v3, v121
	v_fma_f32 v44, -v1, v1, 1.0
	v_max_f32_e32 v44, 0, v44
	v_sqrt_f32_e32 v44, v44
	s_waitcnt lgkmcnt(0)
	v_lshlrev_b32_e32 v3, 16, v3
	v_mul_f32_e32 v2, v2, v44
	ds_write2st64_b32 v110, v1, v2 offset0:108 offset1:173
	v_add_f32_e32 v1, v97, v46
	v_mul_f32_e32 v1, 0xbfb8aa3b, v1
	v_exp_f32_e32 v1, v1
	v_add_f32_e32 v2, v98, v50
	v_mul_f32_e32 v2, 0xbfb8aa3b, v2
	v_exp_f32_e32 v2, v2
	v_add_f32_e32 v1, 1.0, v1
	v_rcp_f32_e32 v1, v1
	v_add_f32_e32 v2, 1.0, v2
	v_rcp_f32_e32 v2, v2
	v_mul_f32_e32 v1, v105, v1
	v_mul_f32_e32 v1, 0x3fb8aa3b, v1
	v_exp_f32_e32 v1, v1
	v_mul_f32_e32 v2, v2, v3
	v_fma_f32 v44, -v1, v1, 1.0
	v_max_f32_e32 v44, 0, v44
	v_sqrt_f32_e32 v44, v44
	s_nop 0
	v_mul_f32_e32 v2, v2, v44
	ds_write_b32 v111, v1 offset:27648
	ds_write_b32 v111, v2 offset:44288
	v_add_f32_e32 v1, v97, v47
	v_mul_f32_e32 v1, 0xbfb8aa3b, v1
	v_exp_f32_e32 v1, v1
	v_add_f32_e32 v2, v98, v51
	v_mul_f32_e32 v2, 0xbfb8aa3b, v2
	v_exp_f32_e32 v2, v2
	v_add_f32_e32 v1, 1.0, v1
	v_rcp_f32_e32 v1, v1
	ds_read_u16 v3, v122
	v_add_f32_e32 v2, 1.0, v2
	v_rcp_f32_e32 v2, v2
	v_mul_f32_e32 v1, v105, v1
	v_mul_f32_e32 v1, 0x3fb8aa3b, v1
	v_exp_f32_e32 v1, v1
	s_waitcnt lgkmcnt(0)
	v_lshlrev_b32_e32 v3, 16, v3
	v_mul_f32_e32 v2, v2, v3
	ds_read_u16 v3, v124
	v_fma_f32 v44, -v1, v1, 1.0
	v_max_f32_e32 v44, 0, v44
	v_sqrt_f32_e32 v44, v44
	s_waitcnt lgkmcnt(0)
	v_lshlrev_b32_e32 v3, 16, v3
	v_mul_f32_e32 v2, v44, v2
	ds_write2st64_b32 v112, v1, v2 offset0:108 offset1:173
	ds_read_b128 v[48:51], v123 offset:18432
	ds_read_b128 v[44:47], v123 offset:9216
	s_waitcnt lgkmcnt(1)
	v_mfma_f32_16x16x32_bf16 v[52:55], v[40:43], v[48:51], 0
	ds_read_b128 v[48:51], v123 offset:9280
	s_waitcnt lgkmcnt(1)
	v_mfma_f32_16x16x32_bf16 v[44:47], v[40:43], v[44:47], 0
	s_waitcnt lgkmcnt(0)
	v_mfma_f32_16x16x32_bf16 v[48:51], v[36:39], v[48:51], v[44:47]
	s_nop 5
	ds_read_b128 v[44:47], v123 offset:18496
	s_nop 0
	v_add_f32_e32 v1, v99, v48
	v_mul_f32_e32 v1, 0xbfb8aa3b, v1
	v_exp_f32_e32 v1, v1
	s_waitcnt lgkmcnt(0)
	v_mfma_f32_16x16x32_bf16 v[44:47], v[36:39], v[44:47], v[52:55]
	v_add_f32_e32 v1, 1.0, v1
	v_rcp_f32_e32 v1, v1
	s_nop 0
	v_mul_f32_e32 v1, v106, v1
	s_nop 3
	v_add_f32_e32 v2, v100, v44
	v_mul_f32_e32 v2, 0xbfb8aa3b, v2
	v_mul_f32_e32 v1, 0x3fb8aa3b, v1
	v_exp_f32_e32 v2, v2
	v_exp_f32_e32 v1, v1
	v_add_f32_e32 v2, 1.0, v2
	v_fma_f32 v44, -v1, v1, 1.0
	v_rcp_f32_e32 v2, v2
	v_max_f32_e32 v44, 0, v44
	v_sqrt_f32_e32 v44, v44
	v_mul_f32_e32 v2, v2, v3
	v_mul_f32_e32 v2, v2, v44
	ds_write_b32 v109, v1 offset:27712
	ds_write_b32 v109, v2 offset:44352
	v_add_f32_e32 v1, v99, v49
	v_mul_f32_e32 v1, 0xbfb8aa3b, v1
	v_exp_f32_e32 v1, v1
	v_add_f32_e32 v2, v100, v45
	v_mul_f32_e32 v2, 0xbfb8aa3b, v2
	v_exp_f32_e32 v2, v2
	v_add_f32_e32 v1, 1.0, v1
	v_rcp_f32_e32 v1, v1
	ds_read_u16 v3, v125
	v_add_f32_e32 v2, 1.0, v2
	v_rcp_f32_e32 v2, v2
	v_mul_f32_e32 v1, v106, v1
	v_mul_f32_e32 v1, 0x3fb8aa3b, v1
	v_exp_f32_e32 v1, v1
	s_waitcnt lgkmcnt(0)
	v_lshlrev_b32_e32 v3, 16, v3
	v_mul_f32_e32 v2, v2, v3
	v_fma_f32 v44, -v1, v1, 1.0
	v_max_f32_e32 v44, 0, v44
	v_sqrt_f32_e32 v44, v44
	s_nop 0
	v_mul_f32_e32 v2, v2, v44
	ds_write_b32 v113, v1 offset:27712
	ds_write_b32 v113, v2 offset:44352
	v_add_f32_e32 v1, v99, v50
	v_mul_f32_e32 v1, 0xbfb8aa3b, v1
	v_exp_f32_e32 v1, v1
	v_add_f32_e32 v2, v100, v46
	v_mul_f32_e32 v2, 0xbfb8aa3b, v2
	v_exp_f32_e32 v2, v2
	v_add_f32_e32 v1, 1.0, v1
	v_rcp_f32_e32 v1, v1
	ds_read_u16 v3, v126
	v_add_f32_e32 v2, 1.0, v2
	v_rcp_f32_e32 v2, v2
	v_mul_f32_e32 v1, v106, v1
	v_mul_f32_e32 v1, 0x3fb8aa3b, v1
	v_exp_f32_e32 v1, v1
	s_waitcnt lgkmcnt(0)
	v_lshlrev_b32_e32 v3, 16, v3
	v_mul_f32_e32 v2, v2, v3
	v_fma_f32 v44, -v1, v1, 1.0
	v_max_f32_e32 v44, 0, v44
	v_sqrt_f32_e32 v44, v44
	s_nop 0
	v_mul_f32_e32 v2, v2, v44
	ds_write_b32 v111, v1 offset:27712
	ds_write_b32 v111, v2 offset:44352
	v_add_f32_e32 v1, v99, v51
	v_mul_f32_e32 v1, 0xbfb8aa3b, v1
	v_exp_f32_e32 v1, v1
	ds_read_u16 v3, v127
	v_add_f32_e32 v1, 1.0, v1
	v_rcp_f32_e32 v2, v1
	v_add_f32_e32 v1, v100, v47
	v_mul_f32_e32 v1, 0xbfb8aa3b, v1
	v_exp_f32_e32 v1, v1
	v_mul_f32_e32 v2, v106, v2
	v_mul_f32_e32 v2, 0x3fb8aa3b, v2
	v_exp_f32_e32 v2, v2
	v_add_f32_e32 v1, 1.0, v1
	v_rcp_f32_e32 v1, v1
	s_waitcnt lgkmcnt(0)
	v_lshlrev_b32_e32 v3, 16, v3
	v_fma_f32 v44, -v2, v2, 1.0
	v_max_f32_e32 v44, 0, v44
	v_sqrt_f32_e32 v44, v44
	v_mul_f32_e32 v1, v1, v3
	v_mul_f32_e32 v1, v44, v1
	ds_write_b32 v114, v2 offset:27712
	ds_write_b32 v114, v1 offset:44352
	ds_read_b128 v[44:47], v128 offset:9216
	ds_read_b128 v[52:55], v128 offset:9280
	s_waitcnt lgkmcnt(1)
	v_mfma_f32_16x16x32_bf16 v[44:47], v[40:43], v[44:47], 0
	ds_read_b128 v[48:51], v128 offset:18432
	ds_read_u16 v3, v129
	s_waitcnt lgkmcnt(0)
	v_lshlrev_b32_e32 v3, 16, v3
	v_mfma_f32_16x16x32_bf16 v[44:47], v[36:39], v[52:55], v[44:47]
	ds_read_b128 v[52:55], v128 offset:18496
	v_mfma_f32_16x16x32_bf16 v[48:51], v[40:43], v[48:51], 0
	s_waitcnt lgkmcnt(0)
	v_mfma_f32_16x16x32_bf16 v[48:51], v[36:39], v[52:55], v[48:51]
	s_nop 3
	v_add_f32_e32 v1, v101, v44
	v_mul_f32_e32 v1, 0xbfb8aa3b, v1
	v_exp_f32_e32 v1, v1
	s_nop 0
	v_add_f32_e32 v1, 1.0, v1
	v_rcp_f32_e32 v1, v1
	v_add_f32_e32 v2, v102, v48
	v_mul_f32_e32 v2, 0xbfb8aa3b, v2
	v_exp_f32_e32 v2, v2
	v_mul_f32_e32 v1, v107, v1
	v_mul_f32_e32 v1, 0x3fb8aa3b, v1
	v_exp_f32_e32 v1, v1
	v_add_f32_e32 v2, 1.0, v2
	v_rcp_f32_e32 v2, v2
	v_fma_f32 v44, -v1, v1, 1.0
	v_max_f32_e32 v44, 0, v44
	v_sqrt_f32_e32 v44, v44
	v_mul_f32_e32 v2, v2, v3
	v_mul_f32_e32 v2, v2, v44
	ds_write_b32 v109, v1 offset:27776
	ds_write_b32 v109, v2 offset:44416
	v_add_f32_e32 v1, v101, v45
	v_mul_f32_e32 v1, 0xbfb8aa3b, v1
	v_exp_f32_e32 v1, v1
	v_add_f32_e32 v2, v102, v49
	v_mul_f32_e32 v2, 0xbfb8aa3b, v2
	v_exp_f32_e32 v2, v2
	v_add_f32_e32 v1, 1.0, v1
	v_rcp_f32_e32 v1, v1
	ds_read_u16 v3, v130
	v_add_f32_e32 v2, 1.0, v2
	v_rcp_f32_e32 v2, v2
	v_mul_f32_e32 v1, v107, v1
	v_mul_f32_e32 v1, 0x3fb8aa3b, v1
	v_exp_f32_e32 v1, v1
	s_waitcnt lgkmcnt(0)
	v_lshlrev_b32_e32 v3, 16, v3
	v_mul_f32_e32 v2, v2, v3
	v_fma_f32 v44, -v1, v1, 1.0
	v_max_f32_e32 v44, 0, v44
	v_sqrt_f32_e32 v44, v44
	s_nop 0
	v_mul_f32_e32 v2, v2, v44
	ds_write_b32 v113, v1 offset:27776
	ds_write_b32 v113, v2 offset:44416
	v_add_f32_e32 v1, v101, v46
	v_mul_f32_e32 v1, 0xbfb8aa3b, v1
	v_exp_f32_e32 v1, v1
	v_add_f32_e32 v2, v102, v50
	v_mul_f32_e32 v2, 0xbfb8aa3b, v2
	v_exp_f32_e32 v2, v2
	v_add_f32_e32 v1, 1.0, v1
	v_rcp_f32_e32 v1, v1
	ds_read_u16 v3, v131
	v_add_f32_e32 v2, 1.0, v2
	v_rcp_f32_e32 v2, v2
	v_mul_f32_e32 v1, v107, v1
	v_mul_f32_e32 v1, 0x3fb8aa3b, v1
	v_exp_f32_e32 v1, v1
	s_waitcnt lgkmcnt(0)
	v_lshlrev_b32_e32 v3, 16, v3
	v_mul_f32_e32 v2, v2, v3
	v_fma_f32 v44, -v1, v1, 1.0
	v_max_f32_e32 v44, 0, v44
	v_sqrt_f32_e32 v44, v44
	s_nop 0
	v_mul_f32_e32 v2, v2, v44
	ds_write_b32 v111, v1 offset:27776
	ds_write_b32 v111, v2 offset:44416
	v_add_f32_e32 v1, v101, v47
	v_mul_f32_e32 v1, 0xbfb8aa3b, v1
	v_exp_f32_e32 v1, v1
	v_add_f32_e32 v2, v102, v51
	v_mul_f32_e32 v2, 0xbfb8aa3b, v2
	v_exp_f32_e32 v2, v2
	v_add_f32_e32 v1, 1.0, v1
	v_rcp_f32_e32 v1, v1
	ds_read_u16 v3, v132
	v_add_f32_e32 v2, 1.0, v2
	v_rcp_f32_e32 v2, v2
	v_mul_f32_e32 v1, v107, v1
	v_mul_f32_e32 v1, 0x3fb8aa3b, v1
	v_exp_f32_e32 v1, v1
	s_waitcnt lgkmcnt(0)
	v_lshlrev_b32_e32 v3, 16, v3
	v_mul_f32_e32 v2, v2, v3
	v_fma_f32 v44, -v1, v1, 1.0
	v_max_f32_e32 v44, 0, v44
	v_sqrt_f32_e32 v44, v44
	s_nop 0
	v_mul_f32_e32 v2, v44, v2
	ds_write_b32 v114, v1 offset:27776
	ds_write_b32 v114, v2 offset:44416
	ds_read_b128 v[44:47], v133 offset:9216
	ds_read_b128 v[48:51], v133 offset:18432
	s_waitcnt lgkmcnt(1)
	v_mfma_f32_16x16x32_bf16 v[44:47], v[40:43], v[44:47], 0
	ds_read_u16 v3, v134
	s_waitcnt lgkmcnt(0)
	v_lshlrev_b32_e32 v3, 16, v3
	v_mfma_f32_16x16x32_bf16 v[48:51], v[40:43], v[48:51], 0
	ds_read_b128 v[40:43], v133 offset:9280
	s_waitcnt lgkmcnt(0)
	v_mfma_f32_16x16x32_bf16 v[40:43], v[36:39], v[40:43], v[44:47]
	s_nop 2
	ds_read_b128 v[44:47], v133 offset:18496
	s_waitcnt lgkmcnt(0)
	v_mfma_f32_16x16x32_bf16 v[36:39], v[36:39], v[44:47], v[48:51]
	s_nop 1
	v_add_f32_e32 v1, v103, v40
	v_mul_f32_e32 v1, 0xbfb8aa3b, v1
	v_exp_f32_e32 v1, v1
	s_nop 2
	v_add_f32_e32 v2, v104, v36
	v_mul_f32_e32 v2, 0xbfb8aa3b, v2
	v_exp_f32_e32 v2, v2
	v_add_f32_e32 v1, 1.0, v1
	v_rcp_f32_e32 v1, v1
	v_add_f32_e32 v2, 1.0, v2
	v_rcp_f32_e32 v2, v2
	v_mul_f32_e32 v1, v108, v1
	v_mul_f32_e32 v1, 0x3fb8aa3b, v1
	v_exp_f32_e32 v1, v1
	v_mul_f32_e32 v2, v2, v3
	v_fma_f32 v36, -v1, v1, 1.0
	v_max_f32_e32 v36, 0, v36
	v_sqrt_f32_e32 v36, v36
	s_nop 0
	v_mul_f32_e32 v2, v2, v36
	ds_write_b32 v109, v1 offset:27840
	ds_write_b32 v109, v2 offset:44480
	v_add_f32_e32 v1, v103, v41
	v_mul_f32_e32 v1, 0xbfb8aa3b, v1
	v_exp_f32_e32 v1, v1
	v_add_f32_e32 v2, v104, v37
	v_mul_f32_e32 v2, 0xbfb8aa3b, v2
	v_exp_f32_e32 v2, v2
	v_add_f32_e32 v1, 1.0, v1
	v_rcp_f32_e32 v1, v1
	ds_read_u16 v3, v135
	v_add_f32_e32 v2, 1.0, v2
	v_rcp_f32_e32 v2, v2
	v_mul_f32_e32 v1, v108, v1
	v_mul_f32_e32 v1, 0x3fb8aa3b, v1
	v_exp_f32_e32 v1, v1
	s_waitcnt lgkmcnt(0)
	v_lshlrev_b32_e32 v3, 16, v3
	v_mul_f32_e32 v2, v2, v3
	v_fma_f32 v36, -v1, v1, 1.0
	v_max_f32_e32 v36, 0, v36
	v_sqrt_f32_e32 v36, v36
	s_nop 0
	v_mul_f32_e32 v2, v2, v36
	ds_write_b32 v113, v1 offset:27840
	ds_write_b32 v113, v2 offset:44480
	v_add_f32_e32 v1, v103, v42
	v_mul_f32_e32 v1, 0xbfb8aa3b, v1
	v_exp_f32_e32 v1, v1
	v_add_f32_e32 v2, v104, v38
	v_mul_f32_e32 v2, 0xbfb8aa3b, v2
	v_exp_f32_e32 v2, v2
	v_add_f32_e32 v1, 1.0, v1
	v_rcp_f32_e32 v1, v1
	ds_read_u16 v3, v136
	v_add_f32_e32 v2, 1.0, v2
	v_rcp_f32_e32 v2, v2
	v_mul_f32_e32 v1, v108, v1
	v_mul_f32_e32 v1, 0x3fb8aa3b, v1
	v_exp_f32_e32 v1, v1
	s_waitcnt lgkmcnt(0)
	v_lshlrev_b32_e32 v3, 16, v3
	v_mul_f32_e32 v2, v2, v3
	v_fma_f32 v36, -v1, v1, 1.0
	v_max_f32_e32 v36, 0, v36
	v_sqrt_f32_e32 v36, v36
	s_nop 0
	v_mul_f32_e32 v2, v2, v36
	ds_write_b32 v111, v1 offset:27840
	ds_write_b32 v111, v2 offset:44480
	v_add_f32_e32 v1, v103, v43
	v_mul_f32_e32 v1, 0xbfb8aa3b, v1
	v_exp_f32_e32 v1, v1
	ds_read_u16 v3, v137
	v_add_f32_e32 v1, 1.0, v1
	v_rcp_f32_e32 v2, v1
	v_add_f32_e32 v1, v104, v39
	v_mul_f32_e32 v1, 0xbfb8aa3b, v1
	v_exp_f32_e32 v1, v1
	v_mul_f32_e32 v2, v108, v2
	v_mul_f32_e32 v2, 0x3fb8aa3b, v2
	v_exp_f32_e32 v2, v2
	v_add_f32_e32 v1, 1.0, v1
	v_rcp_f32_e32 v1, v1
	s_waitcnt lgkmcnt(0)
	v_lshlrev_b32_e32 v3, 16, v3
	v_fma_f32 v36, -v2, v2, 1.0
	v_max_f32_e32 v36, 0, v36
	v_sqrt_f32_e32 v36, v36
	v_mul_f32_e32 v1, v1, v3
	v_mul_f32_e32 v1, v36, v1
	ds_write_b32 v114, v2 offset:27840
	ds_write_b32 v114, v1 offset:44480
	s_waitcnt lgkmcnt(0)
	s_barrier
	s_and_b64 s[28:29], s[16:17], exec
	s_cselect_b32 s35, 0, 0x3ffc
	s_cselect_b32 s19, 1, -1
	s_mulk_i32 s19, 0x104
	v_readfirstlane_b32 s32, v92
	s_lshr_b32 s32, s32, 6
	s_and_b32 s32, s32, 3
	v_and_b32_e32 v147, 63, v92
	v_lshl_add_u32 v176, v147, 3, s56
	v_lshl_add_u32 v147, v147, 2, s56
	s_mul_i32 s23, s19, s32
	s_lshl_b32 s23, s23, 4
	s_add_i32 s23, s23, s35
	v_add_u32_e32 v1, s23, v147
	v_add_u32_e32 v2, s19, v1
	v_add_u32_e32 v3, s19, v2
	v_add_u32_e32 v36, s19, v3
	v_add_u32_e32 v37, s19, v36
	v_add_u32_e32 v38, s19, v37
	v_add_u32_e32 v39, s19, v38
	v_add_u32_e32 v40, s19, v39
	v_add_u32_e32 v41, s19, v40
	v_add_u32_e32 v42, s19, v41
	v_add_u32_e32 v43, s19, v42
	v_add_u32_e32 v64, s19, v43
	v_add_u32_e32 v65, s19, v64
	v_add_u32_e32 v66, s19, v65
	v_add_u32_e32 v67, s19, v66
	v_add_u32_e32 v68, s19, v67
	ds_read2st64_b32 v[148:149], v1 offset0:108 offset1:173
	ds_read2st64_b32 v[150:151], v2 offset0:108 offset1:173
	ds_read2st64_b32 v[152:153], v3 offset0:108 offset1:173
	ds_read2st64_b32 v[154:155], v36 offset0:108 offset1:173
	ds_read2st64_b32 v[156:157], v37 offset0:108 offset1:173
	ds_read2st64_b32 v[158:159], v38 offset0:108 offset1:173
	ds_read2st64_b32 v[160:161], v39 offset0:108 offset1:173
	ds_read2st64_b32 v[162:163], v40 offset0:108 offset1:173
	ds_read2st64_b32 v[164:165], v41 offset0:108 offset1:173
	ds_read2st64_b32 v[166:167], v42 offset0:108 offset1:173
	ds_read2st64_b32 v[168:169], v43 offset0:108 offset1:173
	ds_read2st64_b32 v[170:171], v64 offset0:108 offset1:173
	ds_read2st64_b32 v[242:243], v65 offset0:108 offset1:173
	ds_read2st64_b32 v[244:245], v66 offset0:108 offset1:173
	ds_read2st64_b32 v[246:247], v67 offset0:108 offset1:173
	ds_read2st64_b32 v[248:249], v68 offset0:108 offset1:173
	s_lshl_b32 s18, s32, 9
	v_add_u32_e32 v139, s18, v176
	s_waitcnt lgkmcnt(14)
	v_fmac_f32_e32 v151, v150, v149
	v_mul_f32_e32 v150, v150, v148
	s_waitcnt lgkmcnt(13)
	v_fmac_f32_e32 v153, v152, v151
	v_mul_f32_e32 v152, v152, v150
	s_waitcnt lgkmcnt(12)
	v_fmac_f32_e32 v155, v154, v153
	v_mul_f32_e32 v154, v154, v152
	s_waitcnt lgkmcnt(11)
	v_fmac_f32_e32 v157, v156, v155
	v_mul_f32_e32 v156, v156, v154
	s_waitcnt lgkmcnt(10)
	v_fmac_f32_e32 v159, v158, v157
	v_mul_f32_e32 v158, v158, v156
	s_waitcnt lgkmcnt(9)
	v_fmac_f32_e32 v161, v160, v159
	v_mul_f32_e32 v160, v160, v158
	s_waitcnt lgkmcnt(8)
	v_fmac_f32_e32 v163, v162, v161
	v_mul_f32_e32 v162, v162, v160
	s_waitcnt lgkmcnt(7)
	v_fmac_f32_e32 v165, v164, v163
	v_mul_f32_e32 v164, v164, v162
	s_waitcnt lgkmcnt(6)
	v_fmac_f32_e32 v167, v166, v165
	v_mul_f32_e32 v166, v166, v164
	s_waitcnt lgkmcnt(5)
	v_fmac_f32_e32 v169, v168, v167
	v_mul_f32_e32 v168, v168, v166
	s_waitcnt lgkmcnt(4)
	v_fmac_f32_e32 v171, v170, v169
	v_mul_f32_e32 v170, v170, v168
	s_waitcnt lgkmcnt(3)
	v_fmac_f32_e32 v243, v242, v171
	v_mul_f32_e32 v242, v242, v170
	s_waitcnt lgkmcnt(2)
	v_fmac_f32_e32 v245, v244, v243
	v_mul_f32_e32 v244, v244, v242
	s_waitcnt lgkmcnt(1)
	v_fmac_f32_e32 v247, v246, v245
	v_mul_f32_e32 v246, v246, v244
	s_waitcnt lgkmcnt(0)
	v_fmac_f32_e32 v249, v248, v247
	v_mul_f32_e32 v248, v248, v246
	ds_write_b64 v139, v[248:249] offset:61440
	s_cmp_lg_u32 s34, 0
	s_cbranch_scc1 .Lps_skipcw_p
	s_cmp_lg_u32 s32, 0
	s_cbranch_scc1 .Lps_skipcw_p
	ds_write_b32 v147, v91 offset:63488
.Lps_skipcw_p:
	s_waitcnt lgkmcnt(0)
	s_barrier
	ds_read_b64 v[70:71], v176 offset:61440
	ds_read_b64 v[72:73], v176 offset:61952
	ds_read_b64 v[74:75], v176 offset:62464
	ds_read_b64 v[140:141], v176 offset:62976
	s_cmp_lg_u32 s34, 0
	s_cbranch_scc1 .Lps_skipcr_p
	ds_read_b32 v91, v147 offset:63488
.Lps_skipcr_p:
	s_waitcnt lgkmcnt(0)
	v_fma_f32 v142, v70, v91, v71
	v_fma_f32 v143, v72, v142, v73
	v_fma_f32 v144, v74, v143, v75
	v_fma_f32 v145, v140, v144, v141
	v_mov_b32_e32 v146, v91
	s_cmp_eq_u32 s32, 1
	s_cselect_b64 vcc, -1, 0
	v_cndmask_b32_e32 v146, v146, v142, vcc
	s_cmp_eq_u32 s32, 2
	s_cselect_b64 vcc, -1, 0
	v_cndmask_b32_e32 v146, v146, v143, vcc
	s_cmp_eq_u32 s32, 3
	s_cselect_b64 vcc, -1, 0
	v_cndmask_b32_e32 v146, v146, v144, vcc
	v_mov_b32_e32 v91, v145
	v_fmac_f32_e32 v149, v148, v146
	ds_write_b32 v1, v149 offset:44288
	v_fmac_f32_e32 v151, v150, v146
	ds_write_b32 v2, v151 offset:44288
	v_fmac_f32_e32 v153, v152, v146
	ds_write_b32 v3, v153 offset:44288
	v_fmac_f32_e32 v155, v154, v146
	ds_write_b32 v36, v155 offset:44288
	v_fmac_f32_e32 v157, v156, v146
	ds_write_b32 v37, v157 offset:44288
	v_fmac_f32_e32 v159, v158, v146
	ds_write_b32 v38, v159 offset:44288
	v_fmac_f32_e32 v161, v160, v146
	ds_write_b32 v39, v161 offset:44288
	v_fmac_f32_e32 v163, v162, v146
	ds_write_b32 v40, v163 offset:44288
	v_fmac_f32_e32 v165, v164, v146
	ds_write_b32 v41, v165 offset:44288
	v_fmac_f32_e32 v167, v166, v146
	ds_write_b32 v42, v167 offset:44288
	v_fmac_f32_e32 v169, v168, v146
	ds_write_b32 v43, v169 offset:44288
	v_fmac_f32_e32 v171, v170, v146
	ds_write_b32 v64, v171 offset:44288
	v_fmac_f32_e32 v243, v242, v146
	ds_write_b32 v65, v243 offset:44288
	v_fmac_f32_e32 v245, v244, v146
	ds_write_b32 v66, v245 offset:44288
	v_fmac_f32_e32 v247, v246, v146
	ds_write_b32 v67, v247 offset:44288
	v_fmac_f32_e32 v249, v248, v146
	ds_write_b32 v68, v249 offset:44288

.LBB0_305:
	s_waitcnt lgkmcnt(0)
	s_barrier
	ds_read_b128 v[40:43], v117
	ds_read_b128 v[36:39], v117 offset:64
	ds_read_b128 v[44:47], v118 offset:9216
	ds_read_b128 v[48:51], v118 offset:18432
	ds_read_b128 v[52:55], v118 offset:9280
	s_waitcnt lgkmcnt(2)
	v_mfma_f32_16x16x32_bf16 v[44:47], v[40:43], v[44:47], 0
	ds_read_u16 v3, v119
	s_waitcnt lgkmcnt(0)
	v_lshlrev_b32_e32 v3, 16, v3
	v_mfma_f32_16x16x32_bf16 v[44:47], v[36:39], v[52:55], v[44:47]
	ds_read_b128 v[52:55], v118 offset:18496
	v_mfma_f32_16x16x32_bf16 v[48:51], v[40:43], v[48:51], 0
	s_waitcnt lgkmcnt(0)
	v_mfma_f32_16x16x32_bf16 v[48:51], v[36:39], v[52:55], v[48:51]
	s_nop 3
	v_add_f32_e32 v1, v97, v44
	v_mul_f32_e32 v1, 0xbfb8aa3b, v1
	v_exp_f32_e32 v1, v1
	s_nop 0
	v_add_f32_e32 v1, 1.0, v1
	v_rcp_f32_e32 v1, v1
	v_add_f32_e32 v2, v98, v48
	v_mul_f32_e32 v2, 0xbfb8aa3b, v2
	v_exp_f32_e32 v2, v2
	v_mul_f32_e32 v1, v105, v1
	v_mul_f32_e32 v1, 0x3fb8aa3b, v1
	v_exp_f32_e32 v1, v1
	v_add_f32_e32 v2, 1.0, v2
	v_rcp_f32_e32 v2, v2
	v_fma_f32 v44, -v1, v1, 1.0
	v_max_f32_e32 v44, 0, v44
	v_sqrt_f32_e32 v44, v44
	v_mul_f32_e32 v2, v2, v3
	v_mul_f32_e32 v2, v2, v44
	ds_write_b32 v109, v1 offset:27648
	ds_write_b32 v109, v2 offset:44288
	v_add_f32_e32 v1, v97, v45
	v_mul_f32_e32 v1, 0xbfb8aa3b, v1
	v_exp_f32_e32 v1, v1
	v_add_f32_e32 v2, v98, v49
	v_mul_f32_e32 v2, 0xbfb8aa3b, v2
	v_exp_f32_e32 v2, v2
	v_add_f32_e32 v1, 1.0, v1
	v_rcp_f32_e32 v1, v1
	ds_read_u16 v3, v120
	v_add_f32_e32 v2, 1.0, v2
	v_rcp_f32_e32 v2, v2
	v_mul_f32_e32 v1, v105, v1
	v_mul_f32_e32 v1, 0x3fb8aa3b, v1
	v_exp_f32_e32 v1, v1
	s_waitcnt lgkmcnt(0)
	v_lshlrev_b32_e32 v3, 16, v3
	v_mul_f32_e32 v2, v2, v3
	ds_read_u16 v3, v121
	v_fma_f32 v44, -v1, v1, 1.0
	v_max_f32_e32 v44, 0, v44
	v_sqrt_f32_e32 v44, v44
	s_waitcnt lgkmcnt(0)
	v_lshlrev_b32_e32 v3, 16, v3
	v_mul_f32_e32 v2, v2, v44
	ds_write2st64_b32 v110, v1, v2 offset0:108 offset1:173
	v_add_f32_e32 v1, v97, v46
	v_mul_f32_e32 v1, 0xbfb8aa3b, v1
	v_exp_f32_e32 v1, v1
	v_add_f32_e32 v2, v98, v50
	v_mul_f32_e32 v2, 0xbfb8aa3b, v2
	v_exp_f32_e32 v2, v2
	v_add_f32_e32 v1, 1.0, v1
	v_rcp_f32_e32 v1, v1
	v_add_f32_e32 v2, 1.0, v2
	v_rcp_f32_e32 v2, v2
	v_mul_f32_e32 v1, v105, v1
	v_mul_f32_e32 v1, 0x3fb8aa3b, v1
	v_exp_f32_e32 v1, v1
	v_mul_f32_e32 v2, v2, v3
	v_fma_f32 v44, -v1, v1, 1.0
	v_max_f32_e32 v44, 0, v44
	v_sqrt_f32_e32 v44, v44
	s_nop 0
	v_mul_f32_e32 v2, v2, v44
	ds_write_b32 v111, v1 offset:27648
	ds_write_b32 v111, v2 offset:44288
	v_add_f32_e32 v1, v97, v47
	v_mul_f32_e32 v1, 0xbfb8aa3b, v1
	v_exp_f32_e32 v1, v1
	v_add_f32_e32 v2, v98, v51
	v_mul_f32_e32 v2, 0xbfb8aa3b, v2
	v_exp_f32_e32 v2, v2
	v_add_f32_e32 v1, 1.0, v1
	v_rcp_f32_e32 v1, v1
	ds_read_u16 v3, v122
	v_add_f32_e32 v2, 1.0, v2
	v_rcp_f32_e32 v2, v2
	v_mul_f32_e32 v1, v105, v1
	v_mul_f32_e32 v1, 0x3fb8aa3b, v1
	v_exp_f32_e32 v1, v1
	s_waitcnt lgkmcnt(0)
	v_lshlrev_b32_e32 v3, 16, v3
	v_mul_f32_e32 v2, v2, v3
	ds_read_u16 v3, v124
	v_fma_f32 v44, -v1, v1, 1.0
	v_max_f32_e32 v44, 0, v44
	v_sqrt_f32_e32 v44, v44
	s_waitcnt lgkmcnt(0)
	v_lshlrev_b32_e32 v3, 16, v3
	v_mul_f32_e32 v2, v44, v2
	ds_write2st64_b32 v112, v1, v2 offset0:108 offset1:173
	ds_read_b128 v[48:51], v123 offset:18432
	ds_read_b128 v[44:47], v123 offset:9216
	s_waitcnt lgkmcnt(1)
	v_mfma_f32_16x16x32_bf16 v[52:55], v[40:43], v[48:51], 0
	ds_read_b128 v[48:51], v123 offset:9280
	s_waitcnt lgkmcnt(1)
	v_mfma_f32_16x16x32_bf16 v[44:47], v[40:43], v[44:47], 0
	s_waitcnt lgkmcnt(0)
	v_mfma_f32_16x16x32_bf16 v[48:51], v[36:39], v[48:51], v[44:47]
	s_nop 5
	ds_read_b128 v[44:47], v123 offset:18496
	s_nop 0
	v_add_f32_e32 v1, v99, v48
	v_mul_f32_e32 v1, 0xbfb8aa3b, v1
	v_exp_f32_e32 v1, v1
	s_waitcnt lgkmcnt(0)
	v_mfma_f32_16x16x32_bf16 v[44:47], v[36:39], v[44:47], v[52:55]
	v_add_f32_e32 v1, 1.0, v1
	v_rcp_f32_e32 v1, v1
	s_nop 0
	v_mul_f32_e32 v1, v106, v1
	s_nop 3
	v_add_f32_e32 v2, v100, v44
	v_mul_f32_e32 v2, 0xbfb8aa3b, v2
	v_mul_f32_e32 v1, 0x3fb8aa3b, v1
	v_exp_f32_e32 v2, v2
	v_exp_f32_e32 v1, v1
	v_add_f32_e32 v2, 1.0, v2
	v_fma_f32 v44, -v1, v1, 1.0
	v_rcp_f32_e32 v2, v2
	v_max_f32_e32 v44, 0, v44
	v_sqrt_f32_e32 v44, v44
	v_mul_f32_e32 v2, v2, v3
	v_mul_f32_e32 v2, v2, v44
	ds_write_b32 v109, v1 offset:27712
	ds_write_b32 v109, v2 offset:44352
	v_add_f32_e32 v1, v99, v49
	v_mul_f32_e32 v1, 0xbfb8aa3b, v1
	v_exp_f32_e32 v1, v1
	v_add_f32_e32 v2, v100, v45
	v_mul_f32_e32 v2, 0xbfb8aa3b, v2
	v_exp_f32_e32 v2, v2
	v_add_f32_e32 v1, 1.0, v1
	v_rcp_f32_e32 v1, v1
	ds_read_u16 v3, v125
	v_add_f32_e32 v2, 1.0, v2
	v_rcp_f32_e32 v2, v2
	v_mul_f32_e32 v1, v106, v1
	v_mul_f32_e32 v1, 0x3fb8aa3b, v1
	v_exp_f32_e32 v1, v1
	s_waitcnt lgkmcnt(0)
	v_lshlrev_b32_e32 v3, 16, v3
	v_mul_f32_e32 v2, v2, v3
	v_fma_f32 v44, -v1, v1, 1.0
	v_max_f32_e32 v44, 0, v44
	v_sqrt_f32_e32 v44, v44
	s_nop 0
	v_mul_f32_e32 v2, v2, v44
	ds_write_b32 v113, v1 offset:27712
	ds_write_b32 v113, v2 offset:44352
	v_add_f32_e32 v1, v99, v50
	v_mul_f32_e32 v1, 0xbfb8aa3b, v1
	v_exp_f32_e32 v1, v1
	v_add_f32_e32 v2, v100, v46
	v_mul_f32_e32 v2, 0xbfb8aa3b, v2
	v_exp_f32_e32 v2, v2
	v_add_f32_e32 v1, 1.0, v1
	v_rcp_f32_e32 v1, v1
	ds_read_u16 v3, v126
	v_add_f32_e32 v2, 1.0, v2
	v_rcp_f32_e32 v2, v2
	v_mul_f32_e32 v1, v106, v1
	v_mul_f32_e32 v1, 0x3fb8aa3b, v1
	v_exp_f32_e32 v1, v1
	s_waitcnt lgkmcnt(0)
	v_lshlrev_b32_e32 v3, 16, v3
	v_mul_f32_e32 v2, v2, v3
	v_fma_f32 v44, -v1, v1, 1.0
	v_max_f32_e32 v44, 0, v44
	v_sqrt_f32_e32 v44, v44
	s_nop 0
	v_mul_f32_e32 v2, v2, v44
	ds_write_b32 v111, v1 offset:27712
	ds_write_b32 v111, v2 offset:44352
	v_add_f32_e32 v1, v99, v51
	v_mul_f32_e32 v1, 0xbfb8aa3b, v1
	v_exp_f32_e32 v1, v1
	ds_read_u16 v3, v127
	v_add_f32_e32 v1, 1.0, v1
	v_rcp_f32_e32 v2, v1
	v_add_f32_e32 v1, v100, v47
	v_mul_f32_e32 v1, 0xbfb8aa3b, v1
	v_exp_f32_e32 v1, v1
	v_mul_f32_e32 v2, v106, v2
	v_mul_f32_e32 v2, 0x3fb8aa3b, v2
	v_exp_f32_e32 v2, v2
	v_add_f32_e32 v1, 1.0, v1
	v_rcp_f32_e32 v1, v1
	s_waitcnt lgkmcnt(0)
	v_lshlrev_b32_e32 v3, 16, v3
	v_fma_f32 v44, -v2, v2, 1.0
	v_max_f32_e32 v44, 0, v44
	v_sqrt_f32_e32 v44, v44
	v_mul_f32_e32 v1, v1, v3
	v_mul_f32_e32 v1, v44, v1
	ds_write_b32 v114, v2 offset:27712
	ds_write_b32 v114, v1 offset:44352
	ds_read_b128 v[44:47], v128 offset:9216
	ds_read_b128 v[52:55], v128 offset:9280
	s_waitcnt lgkmcnt(1)
	v_mfma_f32_16x16x32_bf16 v[44:47], v[40:43], v[44:47], 0
	ds_read_b128 v[48:51], v128 offset:18432
	ds_read_u16 v3, v129
	s_waitcnt lgkmcnt(0)
	v_lshlrev_b32_e32 v3, 16, v3
	v_mfma_f32_16x16x32_bf16 v[44:47], v[36:39], v[52:55], v[44:47]
	ds_read_b128 v[52:55], v128 offset:18496
	v_mfma_f32_16x16x32_bf16 v[48:51], v[40:43], v[48:51], 0
	s_waitcnt lgkmcnt(0)
	v_mfma_f32_16x16x32_bf16 v[48:51], v[36:39], v[52:55], v[48:51]
	s_nop 3
	v_add_f32_e32 v1, v101, v44
	v_mul_f32_e32 v1, 0xbfb8aa3b, v1
	v_exp_f32_e32 v1, v1
	s_nop 0
	v_add_f32_e32 v1, 1.0, v1
	v_rcp_f32_e32 v1, v1
	v_add_f32_e32 v2, v102, v48
	v_mul_f32_e32 v2, 0xbfb8aa3b, v2
	v_exp_f32_e32 v2, v2
	v_mul_f32_e32 v1, v107, v1
	v_mul_f32_e32 v1, 0x3fb8aa3b, v1
	v_exp_f32_e32 v1, v1
	v_add_f32_e32 v2, 1.0, v2
	v_rcp_f32_e32 v2, v2
	v_fma_f32 v44, -v1, v1, 1.0
	v_max_f32_e32 v44, 0, v44
	v_sqrt_f32_e32 v44, v44
	v_mul_f32_e32 v2, v2, v3
	v_mul_f32_e32 v2, v2, v44
	ds_write_b32 v109, v1 offset:27776
	ds_write_b32 v109, v2 offset:44416
	v_add_f32_e32 v1, v101, v45
	v_mul_f32_e32 v1, 0xbfb8aa3b, v1
	v_exp_f32_e32 v1, v1
	v_add_f32_e32 v2, v102, v49
	v_mul_f32_e32 v2, 0xbfb8aa3b, v2
	v_exp_f32_e32 v2, v2
	v_add_f32_e32 v1, 1.0, v1
	v_rcp_f32_e32 v1, v1
	ds_read_u16 v3, v130
	v_add_f32_e32 v2, 1.0, v2
	v_rcp_f32_e32 v2, v2
	v_mul_f32_e32 v1, v107, v1
	v_mul_f32_e32 v1, 0x3fb8aa3b, v1
	v_exp_f32_e32 v1, v1
	s_waitcnt lgkmcnt(0)
	v_lshlrev_b32_e32 v3, 16, v3
	v_mul_f32_e32 v2, v2, v3
	v_fma_f32 v44, -v1, v1, 1.0
	v_max_f32_e32 v44, 0, v44
	v_sqrt_f32_e32 v44, v44
	s_nop 0
	v_mul_f32_e32 v2, v2, v44
	ds_write_b32 v113, v1 offset:27776
	ds_write_b32 v113, v2 offset:44416
	v_add_f32_e32 v1, v101, v46
	v_mul_f32_e32 v1, 0xbfb8aa3b, v1
	v_exp_f32_e32 v1, v1
	v_add_f32_e32 v2, v102, v50
	v_mul_f32_e32 v2, 0xbfb8aa3b, v2
	v_exp_f32_e32 v2, v2
	v_add_f32_e32 v1, 1.0, v1
	v_rcp_f32_e32 v1, v1
	ds_read_u16 v3, v131
	v_add_f32_e32 v2, 1.0, v2
	v_rcp_f32_e32 v2, v2
	v_mul_f32_e32 v1, v107, v1
	v_mul_f32_e32 v1, 0x3fb8aa3b, v1
	v_exp_f32_e32 v1, v1
	s_waitcnt lgkmcnt(0)
	v_lshlrev_b32_e32 v3, 16, v3
	v_mul_f32_e32 v2, v2, v3
	v_fma_f32 v44, -v1, v1, 1.0
	v_max_f32_e32 v44, 0, v44
	v_sqrt_f32_e32 v44, v44
	s_nop 0
	v_mul_f32_e32 v2, v2, v44
	ds_write_b32 v111, v1 offset:27776
	ds_write_b32 v111, v2 offset:44416
	v_add_f32_e32 v1, v101, v47
	v_mul_f32_e32 v1, 0xbfb8aa3b, v1
	v_exp_f32_e32 v1, v1
	v_add_f32_e32 v2, v102, v51
	v_mul_f32_e32 v2, 0xbfb8aa3b, v2
	v_exp_f32_e32 v2, v2
	v_add_f32_e32 v1, 1.0, v1
	v_rcp_f32_e32 v1, v1
	ds_read_u16 v3, v132
	v_add_f32_e32 v2, 1.0, v2
	v_rcp_f32_e32 v2, v2
	v_mul_f32_e32 v1, v107, v1
	v_mul_f32_e32 v1, 0x3fb8aa3b, v1
	v_exp_f32_e32 v1, v1
	s_waitcnt lgkmcnt(0)
	v_lshlrev_b32_e32 v3, 16, v3
	v_mul_f32_e32 v2, v2, v3
	v_fma_f32 v44, -v1, v1, 1.0
	v_max_f32_e32 v44, 0, v44
	v_sqrt_f32_e32 v44, v44
	s_nop 0
	v_mul_f32_e32 v2, v44, v2
	ds_write_b32 v114, v1 offset:27776
	ds_write_b32 v114, v2 offset:44416
	ds_read_b128 v[44:47], v133 offset:9216
	ds_read_b128 v[48:51], v133 offset:18432
	s_waitcnt lgkmcnt(1)
	v_mfma_f32_16x16x32_bf16 v[44:47], v[40:43], v[44:47], 0
	ds_read_u16 v3, v134
	s_waitcnt lgkmcnt(0)
	v_lshlrev_b32_e32 v3, 16, v3
	v_mfma_f32_16x16x32_bf16 v[48:51], v[40:43], v[48:51], 0
	ds_read_b128 v[40:43], v133 offset:9280
	s_waitcnt lgkmcnt(0)
	v_mfma_f32_16x16x32_bf16 v[40:43], v[36:39], v[40:43], v[44:47]
	s_nop 2
	ds_read_b128 v[44:47], v133 offset:18496
	s_waitcnt lgkmcnt(0)
	v_mfma_f32_16x16x32_bf16 v[36:39], v[36:39], v[44:47], v[48:51]
	s_nop 1
	v_add_f32_e32 v1, v103, v40
	v_mul_f32_e32 v1, 0xbfb8aa3b, v1
	v_exp_f32_e32 v1, v1
	s_nop 2
	v_add_f32_e32 v2, v104, v36
	v_mul_f32_e32 v2, 0xbfb8aa3b, v2
	v_exp_f32_e32 v2, v2
	v_add_f32_e32 v1, 1.0, v1
	v_rcp_f32_e32 v1, v1
	v_add_f32_e32 v2, 1.0, v2
	v_rcp_f32_e32 v2, v2
	v_mul_f32_e32 v1, v108, v1
	v_mul_f32_e32 v1, 0x3fb8aa3b, v1
	v_exp_f32_e32 v1, v1
	v_mul_f32_e32 v2, v2, v3
	v_fma_f32 v36, -v1, v1, 1.0
	v_max_f32_e32 v36, 0, v36
	v_sqrt_f32_e32 v36, v36
	s_nop 0
	v_mul_f32_e32 v2, v2, v36
	ds_write_b32 v109, v1 offset:27840
	ds_write_b32 v109, v2 offset:44480
	v_add_f32_e32 v1, v103, v41
	v_mul_f32_e32 v1, 0xbfb8aa3b, v1
	v_exp_f32_e32 v1, v1
	v_add_f32_e32 v2, v104, v37
	v_mul_f32_e32 v2, 0xbfb8aa3b, v2
	v_exp_f32_e32 v2, v2
	v_add_f32_e32 v1, 1.0, v1
	v_rcp_f32_e32 v1, v1
	ds_read_u16 v3, v135
	v_add_f32_e32 v2, 1.0, v2
	v_rcp_f32_e32 v2, v2
	v_mul_f32_e32 v1, v108, v1
	v_mul_f32_e32 v1, 0x3fb8aa3b, v1
	v_exp_f32_e32 v1, v1
	s_waitcnt lgkmcnt(0)
	v_lshlrev_b32_e32 v3, 16, v3
	v_mul_f32_e32 v2, v2, v3
	v_fma_f32 v36, -v1, v1, 1.0
	v_max_f32_e32 v36, 0, v36
	v_sqrt_f32_e32 v36, v36
	s_nop 0
	v_mul_f32_e32 v2, v2, v36
	ds_write_b32 v113, v1 offset:27840
	ds_write_b32 v113, v2 offset:44480
	v_add_f32_e32 v1, v103, v42
	v_mul_f32_e32 v1, 0xbfb8aa3b, v1
	v_exp_f32_e32 v1, v1
	v_add_f32_e32 v2, v104, v38
	v_mul_f32_e32 v2, 0xbfb8aa3b, v2
	v_exp_f32_e32 v2, v2
	v_add_f32_e32 v1, 1.0, v1
	v_rcp_f32_e32 v1, v1
	ds_read_u16 v3, v136
	v_add_f32_e32 v2, 1.0, v2
	v_rcp_f32_e32 v2, v2
	v_mul_f32_e32 v1, v108, v1
	v_mul_f32_e32 v1, 0x3fb8aa3b, v1
	v_exp_f32_e32 v1, v1
	s_waitcnt lgkmcnt(0)
	v_lshlrev_b32_e32 v3, 16, v3
	v_mul_f32_e32 v2, v2, v3
	v_fma_f32 v36, -v1, v1, 1.0
	v_max_f32_e32 v36, 0, v36
	v_sqrt_f32_e32 v36, v36
	s_nop 0
	v_mul_f32_e32 v2, v2, v36
	ds_write_b32 v111, v1 offset:27840
	ds_write_b32 v111, v2 offset:44480
	v_add_f32_e32 v1, v103, v43
	v_mul_f32_e32 v1, 0xbfb8aa3b, v1
	v_exp_f32_e32 v1, v1
	ds_read_u16 v3, v137
	v_add_f32_e32 v1, 1.0, v1
	v_rcp_f32_e32 v2, v1
	v_add_f32_e32 v1, v104, v39
	v_mul_f32_e32 v1, 0xbfb8aa3b, v1
	v_exp_f32_e32 v1, v1
	v_mul_f32_e32 v2, v108, v2
	v_mul_f32_e32 v2, 0x3fb8aa3b, v2
	v_exp_f32_e32 v2, v2
	v_add_f32_e32 v1, 1.0, v1
	v_rcp_f32_e32 v1, v1
	s_waitcnt lgkmcnt(0)
	v_lshlrev_b32_e32 v3, 16, v3
	v_fma_f32 v36, -v2, v2, 1.0
	v_max_f32_e32 v36, 0, v36
	v_sqrt_f32_e32 v36, v36
	v_mul_f32_e32 v1, v1, v3
	v_mul_f32_e32 v1, v36, v1
	ds_write_b32 v114, v2 offset:27840
	ds_write_b32 v114, v1 offset:44480
	s_waitcnt lgkmcnt(0)
	s_barrier
	s_and_b64 s[18:19], s[12:13], exec
	s_cselect_b32 s21, 0, 0x3ffc
	s_cselect_b32 s16, 1, -1
	s_mulk_i32 s16, 0x104
	v_readfirstlane_b32 s32, v92
	s_lshr_b32 s32, s32, 6
	s_and_b32 s32, s32, 3
	v_and_b32_e32 v147, 63, v92
	v_lshl_add_u32 v176, v147, 3, s40
	v_lshl_add_u32 v147, v147, 2, s40
	s_mul_i32 s17, s16, s32
	s_lshl_b32 s17, s17, 4
	s_add_i32 s17, s17, s21
	v_add_u32_e32 v1, s17, v147
	v_add_u32_e32 v2, s16, v1
	v_add_u32_e32 v3, s16, v2
	v_add_u32_e32 v36, s16, v3
	v_add_u32_e32 v37, s16, v36
	v_add_u32_e32 v38, s16, v37
	v_add_u32_e32 v39, s16, v38
	v_add_u32_e32 v40, s16, v39
	v_add_u32_e32 v41, s16, v40
	v_add_u32_e32 v42, s16, v41
	v_add_u32_e32 v43, s16, v42
	v_add_u32_e32 v64, s16, v43
	v_add_u32_e32 v65, s16, v64
	v_add_u32_e32 v66, s16, v65
	v_add_u32_e32 v67, s16, v66
	v_add_u32_e32 v68, s16, v67
	ds_read2st64_b32 v[148:149], v1 offset0:108 offset1:173
	ds_read2st64_b32 v[150:151], v2 offset0:108 offset1:173
	ds_read2st64_b32 v[152:153], v3 offset0:108 offset1:173
	ds_read2st64_b32 v[154:155], v36 offset0:108 offset1:173
	ds_read2st64_b32 v[156:157], v37 offset0:108 offset1:173
	ds_read2st64_b32 v[158:159], v38 offset0:108 offset1:173
	ds_read2st64_b32 v[160:161], v39 offset0:108 offset1:173
	ds_read2st64_b32 v[162:163], v40 offset0:108 offset1:173
	ds_read2st64_b32 v[164:165], v41 offset0:108 offset1:173
	ds_read2st64_b32 v[166:167], v42 offset0:108 offset1:173
	ds_read2st64_b32 v[168:169], v43 offset0:108 offset1:173
	ds_read2st64_b32 v[170:171], v64 offset0:108 offset1:173
	ds_read2st64_b32 v[242:243], v65 offset0:108 offset1:173
	ds_read2st64_b32 v[244:245], v66 offset0:108 offset1:173
	ds_read2st64_b32 v[246:247], v67 offset0:108 offset1:173
	ds_read2st64_b32 v[248:249], v68 offset0:108 offset1:173
	s_lshl_b32 s15, s32, 9
	v_add_u32_e32 v139, s15, v176
	s_waitcnt lgkmcnt(14)
	v_fmac_f32_e32 v151, v150, v149
	v_mul_f32_e32 v150, v150, v148
	s_waitcnt lgkmcnt(13)
	v_fmac_f32_e32 v153, v152, v151
	v_mul_f32_e32 v152, v152, v150
	s_waitcnt lgkmcnt(12)
	v_fmac_f32_e32 v155, v154, v153
	v_mul_f32_e32 v154, v154, v152
	s_waitcnt lgkmcnt(11)
	v_fmac_f32_e32 v157, v156, v155
	v_mul_f32_e32 v156, v156, v154
	s_waitcnt lgkmcnt(10)
	v_fmac_f32_e32 v159, v158, v157
	v_mul_f32_e32 v158, v158, v156
	s_waitcnt lgkmcnt(9)
	v_fmac_f32_e32 v161, v160, v159
	v_mul_f32_e32 v160, v160, v158
	s_waitcnt lgkmcnt(8)
	v_fmac_f32_e32 v163, v162, v161
	v_mul_f32_e32 v162, v162, v160
	s_waitcnt lgkmcnt(7)
	v_fmac_f32_e32 v165, v164, v163
	v_mul_f32_e32 v164, v164, v162
	s_waitcnt lgkmcnt(6)
	v_fmac_f32_e32 v167, v166, v165
	v_mul_f32_e32 v166, v166, v164
	s_waitcnt lgkmcnt(5)
	v_fmac_f32_e32 v169, v168, v167
	v_mul_f32_e32 v168, v168, v166
	s_waitcnt lgkmcnt(4)
	v_fmac_f32_e32 v171, v170, v169
	v_mul_f32_e32 v170, v170, v168
	s_waitcnt lgkmcnt(3)
	v_fmac_f32_e32 v243, v242, v171
	v_mul_f32_e32 v242, v242, v170
	s_waitcnt lgkmcnt(2)
	v_fmac_f32_e32 v245, v244, v243
	v_mul_f32_e32 v244, v244, v242
	s_waitcnt lgkmcnt(1)
	v_fmac_f32_e32 v247, v246, v245
	v_mul_f32_e32 v246, v246, v244
	s_waitcnt lgkmcnt(0)
	v_fmac_f32_e32 v249, v248, v247
	v_mul_f32_e32 v248, v248, v246
	ds_write_b64 v139, v[248:249] offset:61440
	s_cmp_lg_u32 s20, 0
	s_cbranch_scc1 .Lps_skipcw_s
	s_cmp_lg_u32 s32, 0
	s_cbranch_scc1 .Lps_skipcw_s
	ds_write_b32 v147, v91 offset:63488
.Lps_skipcw_s:
	s_waitcnt lgkmcnt(0)
	s_barrier
	ds_read_b64 v[70:71], v176 offset:61440
	ds_read_b64 v[72:73], v176 offset:61952
	ds_read_b64 v[74:75], v176 offset:62464
	ds_read_b64 v[140:141], v176 offset:62976
	s_cmp_lg_u32 s20, 0
	s_cbranch_scc1 .Lps_skipcr_s
	ds_read_b32 v91, v147 offset:63488
.Lps_skipcr_s:
	s_waitcnt lgkmcnt(0)
	v_fma_f32 v142, v70, v91, v71
	v_fma_f32 v143, v72, v142, v73
	v_fma_f32 v144, v74, v143, v75
	v_fma_f32 v145, v140, v144, v141
	v_mov_b32_e32 v146, v91
	s_cmp_eq_u32 s32, 1
	s_cselect_b64 vcc, -1, 0
	v_cndmask_b32_e32 v146, v146, v142, vcc
	s_cmp_eq_u32 s32, 2
	s_cselect_b64 vcc, -1, 0
	v_cndmask_b32_e32 v146, v146, v143, vcc
	s_cmp_eq_u32 s32, 3
	s_cselect_b64 vcc, -1, 0
	v_cndmask_b32_e32 v146, v146, v144, vcc
	v_mov_b32_e32 v91, v145
	v_fmac_f32_e32 v149, v148, v146
	ds_write_b32 v1, v149 offset:44288
	v_fmac_f32_e32 v151, v150, v146
	ds_write_b32 v2, v151 offset:44288
	v_fmac_f32_e32 v153, v152, v146
	ds_write_b32 v3, v153 offset:44288
	v_fmac_f32_e32 v155, v154, v146
	ds_write_b32 v36, v155 offset:44288
	v_fmac_f32_e32 v157, v156, v146
	ds_write_b32 v37, v157 offset:44288
	v_fmac_f32_e32 v159, v158, v146
	ds_write_b32 v38, v159 offset:44288
	v_fmac_f32_e32 v161, v160, v146
	ds_write_b32 v39, v161 offset:44288
	v_fmac_f32_e32 v163, v162, v146
	ds_write_b32 v40, v163 offset:44288
	v_fmac_f32_e32 v165, v164, v146
	ds_write_b32 v41, v165 offset:44288
	v_fmac_f32_e32 v167, v166, v146
	ds_write_b32 v42, v167 offset:44288
	v_fmac_f32_e32 v169, v168, v146
	ds_write_b32 v43, v169 offset:44288
	v_fmac_f32_e32 v171, v170, v146
	ds_write_b32 v64, v171 offset:44288
	v_fmac_f32_e32 v243, v242, v146
	ds_write_b32 v65, v243 offset:44288
	v_fmac_f32_e32 v245, v244, v146
	ds_write_b32 v66, v245 offset:44288
	v_fmac_f32_e32 v247, v246, v146
	ds_write_b32 v67, v247 offset:44288
	v_fmac_f32_e32 v249, v248, v146
	ds_write_b32 v68, v249 offset:44288
	s_branch .LBB0_290
